# v10 + mixA norm-loop loads hoisted (16 loads in flight, counted waits); prep p->bf16 loop pipelined
# speedup vs baseline: 1.0571x; 1.0097x over previous
; __device__ __forceinline__ float gelu_t(float x) { float u = 0.7978845608028654f * (x + 0.044715f * x * x * x); return x * __builtin_amdgcn_rcpf(1.f + __expf(-2.f * u)); }
; __device__ __forceinline__ void mixA_item(const Params& P, int layer, int idx, const bf16_t* z, bf16_t* y, char* lds) {
;     ...
;     const int s = tid >> 1, half = tid & 1;
;     const bf16_t* zr = z + (size_t)(tok0 + s) * LDZ + ZC_AV;
;     float ss = 0.f;
; #pragma unroll 4
;     for (int i = 0; i < 16; ++i) { float v[8]; unpack8(*(const u32x4*)(zr + half * 128 + i * 8), v);
; #pragma unroll
;       for (int e = 0; e < 8; ++e) { const float t = gelu_t(v[e]); ss += t * t; } }
.LBB0_548:
	v_mov_b32 v28, v179
	s_movk_i32 s30, 0xff80
	v_bfe_u32 v29, v28, 1, 7
	v_and_or_b32 v0, v39, s30, v29
	v_mad_i64_i32 v[0:1], s[30:31], v0, s43, 0
	v_and_b32_e32 v30, 1, v28
	v_lshl_or_b32 v0, v30, 8, v0
	v_lshl_add_u64 v[8:9], s[10:11], 0, v[0:1]
	v_mov_b32_e32 v10, 0
	s_mov_b64 s[38:39], 0
	v_add_co_u32_e32 v80, vcc, 0xb761200, v8
	s_nop 1
	v_addc_co_u32_e32 v81, vcc, 0, v9, vcc
	global_load_dwordx4 v[84:87], v[80:81], off
	global_load_dwordx4 v[88:91], v[80:81], off offset:16
	global_load_dwordx4 v[92:95], v[80:81], off offset:32
	global_load_dwordx4 v[96:99], v[80:81], off offset:48
	global_load_dwordx4 v[100:103], v[80:81], off offset:64
	global_load_dwordx4 v[104:107], v[80:81], off offset:80
	global_load_dwordx4 v[108:111], v[80:81], off offset:96
	global_load_dwordx4 v[112:115], v[80:81], off offset:112
	global_load_dwordx4 v[116:119], v[80:81], off offset:128
	global_load_dwordx4 v[120:123], v[80:81], off offset:144
	global_load_dwordx4 v[124:127], v[80:81], off offset:160
	global_load_dwordx4 v[128:131], v[80:81], off offset:176
	global_load_dwordx4 v[132:135], v[80:81], off offset:192
	global_load_dwordx4 v[136:139], v[80:81], off offset:208
	global_load_dwordx4 v[140:143], v[80:81], off offset:224
	global_load_dwordx4 v[144:147], v[80:81], off offset:240
.LBB0_549:
	s_mov_b64 s[30:31], 0xb761200
	s_add_u32 s38, s38, 64
	s_addc_u32 s39, s39, 0
	s_cmp_eq_u32 s38, 64
	s_cbranch_scc1 .Lmixa_n0
	s_cmp_eq_u32 s38, 0x80
	s_cbranch_scc1 .Lmixa_n1
	s_cmp_eq_u32 s38, 0xc0
	s_cbranch_scc1 .Lmixa_n2
	s_waitcnt vmcnt(0)
	v_mov_b32_e32 v12, v132
	v_mov_b32_e32 v13, v133
	v_mov_b32_e32 v14, v134
	v_mov_b32_e32 v15, v135
	v_mov_b32_e32 v16, v136
	v_mov_b32_e32 v17, v137
	v_mov_b32_e32 v18, v138
	v_mov_b32_e32 v19, v139
	v_mov_b32_e32 v4, v140
	v_mov_b32_e32 v5, v141
	v_mov_b32_e32 v6, v142
	v_mov_b32_e32 v7, v143
	v_mov_b32_e32 v0, v144
	v_mov_b32_e32 v1, v145
	v_mov_b32_e32 v2, v146
	v_mov_b32_e32 v3, v147
	s_branch .Lmixa_nj
.Lmixa_n0:
	s_waitcnt vmcnt(12)
	v_mov_b32_e32 v12, v84
	v_mov_b32_e32 v13, v85
	v_mov_b32_e32 v14, v86
	v_mov_b32_e32 v15, v87
	v_mov_b32_e32 v16, v88
	v_mov_b32_e32 v17, v89
	v_mov_b32_e32 v18, v90
	v_mov_b32_e32 v19, v91
	v_mov_b32_e32 v4, v92
	v_mov_b32_e32 v5, v93
	v_mov_b32_e32 v6, v94
	v_mov_b32_e32 v7, v95
	v_mov_b32_e32 v0, v96
	v_mov_b32_e32 v1, v97
	v_mov_b32_e32 v2, v98
	v_mov_b32_e32 v3, v99
	s_branch .Lmixa_nj
.Lmixa_n1:
	s_waitcnt vmcnt(8)
	v_mov_b32_e32 v12, v100
	v_mov_b32_e32 v13, v101
	v_mov_b32_e32 v14, v102
	v_mov_b32_e32 v15, v103
	v_mov_b32_e32 v16, v104
	v_mov_b32_e32 v17, v105
	v_mov_b32_e32 v18, v106
	v_mov_b32_e32 v19, v107
	v_mov_b32_e32 v4, v108
	v_mov_b32_e32 v5, v109
	v_mov_b32_e32 v6, v110
	v_mov_b32_e32 v7, v111
	v_mov_b32_e32 v0, v112
	v_mov_b32_e32 v1, v113
	v_mov_b32_e32 v2, v114
	v_mov_b32_e32 v3, v115
	s_branch .Lmixa_nj
.Lmixa_n2:
	s_waitcnt vmcnt(4)
	v_mov_b32_e32 v12, v116
	v_mov_b32_e32 v13, v117
	v_mov_b32_e32 v14, v118
	v_mov_b32_e32 v15, v119
	v_mov_b32_e32 v16, v120
	v_mov_b32_e32 v17, v121
	v_mov_b32_e32 v18, v122
	v_mov_b32_e32 v19, v123
	v_mov_b32_e32 v4, v124
	v_mov_b32_e32 v5, v125
	v_mov_b32_e32 v6, v126
	v_mov_b32_e32 v7, v127
	v_mov_b32_e32 v0, v128
	v_mov_b32_e32 v1, v129
	v_mov_b32_e32 v2, v130
	v_mov_b32_e32 v3, v131
.Lmixa_nj:
	s_cmpk_eq_i32 s38, 0x100
	v_lshlrev_b32_e32 v11, 16, v12
	v_mul_f32_e32 v20, 0x3d372713, v11
	v_mul_f32_e32 v20, v20, v11
	v_fma_f32 v20, v20, v11, v11
	v_mul_f32_e32 v20, 0x3f4c422a, v20
	v_mul_f32_e32 v20, -2.0, v20
	v_mul_f32_e32 v20, 0x3fb8aa3b, v20
	v_exp_f32_e32 v20, v20
	v_lshlrev_b32_e32 v21, 16, v13
	v_and_b32_e32 v24, 0xffff0000, v15
	v_add_f32_e32 v20, 1.0, v20
	v_rcp_f32_e32 v20, v20
	s_nop 0
	v_mul_f32_e32 v11, v20, v11
	v_and_b32_e32 v20, 0xffff0000, v12
	v_fmac_f32_e32 v10, v11, v11
	v_mul_f32_e32 v11, 0x3d372713, v20
	v_mul_f32_e32 v11, v11, v20
	v_mov_b32_e32 v12, v20
	v_fmac_f32_e32 v12, v11, v12
	v_mul_f32_e32 v11, 0x3f4c422a, v12
	v_mul_f32_e32 v11, -2.0, v11
	v_mul_f32_e32 v11, 0x3fb8aa3b, v11
	v_exp_f32_e32 v11, v11
	v_mov_b32_e32 v12, v21
	v_add_f32_e32 v11, 1.0, v11
	v_rcp_f32_e32 v22, v11
	v_mul_f32_e32 v11, 0x3d372713, v21
	v_mul_f32_e32 v11, v11, v21
	v_fmac_f32_e32 v12, v11, v12
	v_mul_f32_e32 v11, 0x3f4c422a, v12
	v_mul_f32_e32 v11, -2.0, v11
	v_mul_f32_e32 v11, 0x3fb8aa3b, v11
	v_exp_f32_e32 v11, v11
	s_nop 0
	v_add_f32_e32 v11, 1.0, v11
	v_rcp_f32_e32 v23, v11
	v_lshlrev_b32_e32 v11, 16, v14
	v_pk_mul_f32 v[20:21], v[22:23], v[20:21]
	s_nop 0
	v_pk_mul_f32 v[20:21], v[20:21], v[20:21]
	s_nop 0
	v_add_f32_e32 v10, v20, v10
	v_add_f32_e32 v20, v21, v10
	v_and_b32_e32 v10, 0xffff0000, v13
	v_mul_f32_e32 v12, 0x3d372713, v10
	v_mul_f32_e32 v12, v12, v10
	v_mov_b32_e32 v13, v10
	v_fmac_f32_e32 v13, v12, v13
	v_mul_f32_e32 v12, 0x3f4c422a, v13
	v_mul_f32_e32 v13, 0x3d372713, v11
	v_mul_f32_e32 v13, v13, v11
	v_mov_b32_e32 v21, v11
	v_fmac_f32_e32 v21, v13, v21
	v_mul_f32_e32 v13, 0x3f4c422a, v21
	v_mul_f32_e32 v12, -2.0, v12
	v_mul_f32_e32 v13, -2.0, v13
	v_mul_f32_e32 v12, 0x3fb8aa3b, v12
	v_mul_f32_e32 v13, 0x3fb8aa3b, v13
	v_exp_f32_e32 v12, v12
	v_exp_f32_e32 v13, v13
	v_add_f32_e32 v12, 1.0, v12
	v_add_f32_e32 v13, 1.0, v13
	v_rcp_f32_e32 v12, v12
	v_rcp_f32_e32 v13, v13
	s_nop 0
	v_pk_mul_f32 v[10:11], v[12:13], v[10:11]
	s_nop 0
	v_pk_mul_f32 v[10:11], v[10:11], v[10:11]
	s_nop 0
	v_add_f32_e32 v10, v10, v20
	v_add_f32_e32 v20, v11, v10
	v_and_b32_e32 v10, 0xffff0000, v14
	v_mul_f32_e32 v12, 0x3d372713, v10
	v_mul_f32_e32 v12, v12, v10
	v_mov_b32_e32 v13, v10
	v_lshlrev_b32_e32 v11, 16, v15
	v_fmac_f32_e32 v13, v12, v13
	v_mul_f32_e32 v12, 0x3f4c422a, v13
	v_mul_f32_e32 v13, 0x3d372713, v11
; __device__ __forceinline__ float gelu_t(float x) { float u = 0.7978845608028654f * (x + 0.044715f * x * x * x); return x * __builtin_amdgcn_rcpf(1.f + __expf(-2.f * u)); }
; __device__ __forceinline__ void mixA_item(const Params& P, int layer, int idx, const bf16_t* z, bf16_t* y, char* lds) {
;     ...
;     for (int i = 0; i < 16; ++i) { float v[8]; unpack8(*(const u32x4*)(zr + half * 128 + i * 8), v);
; #pragma unroll
;       for (int e = 0; e < 8; ++e) { const float t = gelu_t(v[e]); ss += t * t; } }
	v_mul_f32_e32 v13, v13, v11
	v_mov_b32_e32 v14, v11
	v_fmac_f32_e32 v14, v13, v14
	v_mul_f32_e32 v13, 0x3f4c422a, v14
	v_mul_f32_e32 v12, -2.0, v12
	v_mul_f32_e32 v13, -2.0, v13
	v_mul_f32_e32 v12, 0x3fb8aa3b, v12
	v_mul_f32_e32 v13, 0x3fb8aa3b, v13
	v_exp_f32_e32 v12, v12
	v_exp_f32_e32 v13, v13
	v_and_b32_e32 v15, 0xffff0000, v19
	v_add_f32_e32 v12, 1.0, v12
	v_add_f32_e32 v13, 1.0, v13
	v_rcp_f32_e32 v12, v12
	v_rcp_f32_e32 v13, v13
	s_nop 0
	v_pk_mul_f32 v[10:11], v[12:13], v[10:11]
	s_nop 0
	v_pk_mul_f32 v[10:11], v[10:11], v[10:11]
	s_nop 0
	v_add_f32_e32 v10, v10, v20
	v_add_f32_e32 v14, v11, v10
	v_mul_f32_e32 v10, 0x3d372713, v24
	v_mul_f32_e32 v10, v10, v24
	v_fma_f32 v10, v10, v24, v24
	v_mul_f32_e32 v10, 0x3f4c422a, v10
	v_mul_f32_e32 v10, -2.0, v10
	v_mul_f32_e32 v10, 0x3fb8aa3b, v10
	v_exp_f32_e32 v10, v10
	s_nop 0
	v_add_f32_e32 v10, 1.0, v10
	v_rcp_f32_e32 v10, v10
	s_nop 0
	v_mul_f32_e32 v10, v10, v24
	v_fmac_f32_e32 v14, v10, v10
	v_lshlrev_b32_e32 v10, 16, v16
	v_mul_f32_e32 v11, 0x3d372713, v10
	v_mul_f32_e32 v11, v11, v10
	v_fma_f32 v11, v11, v10, v10
	v_mul_f32_e32 v11, 0x3f4c422a, v11
	v_mul_f32_e32 v11, -2.0, v11
	v_mul_f32_e32 v11, 0x3fb8aa3b, v11
	v_exp_f32_e32 v11, v11
	s_nop 0
	v_add_f32_e32 v11, 1.0, v11
	v_rcp_f32_e32 v11, v11
	s_nop 0
	v_mul_f32_e32 v10, v11, v10
	v_fmac_f32_e32 v14, v10, v10
	v_and_b32_e32 v10, 0xffff0000, v16
	v_mul_f32_e32 v12, 0x3d372713, v10
	v_mul_f32_e32 v12, v12, v10
	v_mov_b32_e32 v13, v10
	v_lshlrev_b32_e32 v11, 16, v17
	v_fmac_f32_e32 v13, v12, v13
	v_mul_f32_e32 v12, 0x3f4c422a, v13
	v_mul_f32_e32 v13, 0x3d372713, v11
	v_mul_f32_e32 v13, v13, v11
	v_mov_b32_e32 v16, v11
	v_fmac_f32_e32 v16, v13, v16
	v_mul_f32_e32 v13, 0x3f4c422a, v16
	v_mul_f32_e32 v12, -2.0, v12
	v_mul_f32_e32 v13, -2.0, v13
	v_mul_f32_e32 v12, 0x3fb8aa3b, v12
	v_mul_f32_e32 v13, 0x3fb8aa3b, v13
	v_exp_f32_e32 v12, v12
	v_exp_f32_e32 v13, v13
	v_add_f32_e32 v12, 1.0, v12
	v_add_f32_e32 v13, 1.0, v13
	v_rcp_f32_e32 v12, v12
	v_rcp_f32_e32 v13, v13
	s_nop 0
	v_pk_mul_f32 v[10:11], v[12:13], v[10:11]
	s_nop 0
	v_pk_mul_f32 v[10:11], v[10:11], v[10:11]
	s_nop 0
	v_add_f32_e32 v10, v10, v14
	v_add_f32_e32 v14, v11, v10
	v_and_b32_e32 v10, 0xffff0000, v17
	v_mul_f32_e32 v12, 0x3d372713, v10
	v_mul_f32_e32 v12, v12, v10
	v_mov_b32_e32 v13, v10
	v_lshlrev_b32_e32 v11, 16, v18
	v_fmac_f32_e32 v13, v12, v13
	v_mul_f32_e32 v12, 0x3f4c422a, v13
	v_mul_f32_e32 v13, 0x3d372713, v11
	v_mul_f32_e32 v13, v13, v11
	v_mov_b32_e32 v16, v11
	v_fmac_f32_e32 v16, v13, v16
	v_mul_f32_e32 v13, 0x3f4c422a, v16
	v_mul_f32_e32 v12, -2.0, v12
	v_mul_f32_e32 v13, -2.0, v13
	v_mul_f32_e32 v12, 0x3fb8aa3b, v12
	v_mul_f32_e32 v13, 0x3fb8aa3b, v13
	v_exp_f32_e32 v12, v12
	v_exp_f32_e32 v13, v13
	v_add_f32_e32 v12, 1.0, v12
	v_add_f32_e32 v13, 1.0, v13
	v_rcp_f32_e32 v12, v12
	v_rcp_f32_e32 v13, v13
	s_nop 0
	v_pk_mul_f32 v[10:11], v[12:13], v[10:11]
	s_nop 0
	v_pk_mul_f32 v[10:11], v[10:11], v[10:11]
	s_nop 0
	v_add_f32_e32 v10, v10, v14
	v_add_f32_e32 v14, v11, v10
	v_and_b32_e32 v10, 0xffff0000, v18
	v_mul_f32_e32 v12, 0x3d372713, v10
	v_mul_f32_e32 v12, v12, v10
	v_mov_b32_e32 v13, v10
	v_lshlrev_b32_e32 v11, 16, v19
	v_fmac_f32_e32 v13, v12, v13
	v_mul_f32_e32 v12, 0x3f4c422a, v13
	v_mul_f32_e32 v13, 0x3d372713, v11
	v_mul_f32_e32 v13, v13, v11
	v_mov_b32_e32 v16, v11
	v_fmac_f32_e32 v16, v13, v16
	v_mul_f32_e32 v13, 0x3f4c422a, v16
	v_mul_f32_e32 v12, -2.0, v12
	v_mul_f32_e32 v13, -2.0, v13
	v_mul_f32_e32 v12, 0x3fb8aa3b, v12
	v_mul_f32_e32 v13, 0x3fb8aa3b, v13
	v_exp_f32_e32 v12, v12
	v_exp_f32_e32 v13, v13
	v_add_f32_e32 v12, 1.0, v12
	v_add_f32_e32 v13, 1.0, v13
	v_rcp_f32_e32 v12, v12
	v_rcp_f32_e32 v13, v13
	s_nop 0
	v_pk_mul_f32 v[10:11], v[12:13], v[10:11]
	s_nop 0
	v_pk_mul_f32 v[10:11], v[10:11], v[10:11]
	s_nop 0
	v_add_f32_e32 v10, v10, v14
	v_add_f32_e32 v14, v11, v10
	v_mul_f32_e32 v10, 0x3d372713, v15
	v_mul_f32_e32 v10, v10, v15
	v_fma_f32 v10, v10, v15, v15
	v_mul_f32_e32 v10, 0x3f4c422a, v10
	v_mul_f32_e32 v10, -2.0, v10
	v_mul_f32_e32 v10, 0x3fb8aa3b, v10
	v_exp_f32_e32 v10, v10
	s_nop 0
	v_add_f32_e32 v10, 1.0, v10
	v_rcp_f32_e32 v10, v10
	s_nop 0
	v_mul_f32_e32 v10, v10, v15
	v_fmac_f32_e32 v14, v10, v10
	v_lshlrev_b32_e32 v10, 16, v4
	v_mul_f32_e32 v11, 0x3d372713, v10
	v_mul_f32_e32 v11, v11, v10
	v_fma_f32 v11, v11, v10, v10
	v_mul_f32_e32 v11, 0x3f4c422a, v11
	v_mul_f32_e32 v11, -2.0, v11
	v_mul_f32_e32 v11, 0x3fb8aa3b, v11
	v_exp_f32_e32 v11, v11
	v_and_b32_e32 v15, 0xffff0000, v7
	v_add_f32_e32 v11, 1.0, v11
	v_rcp_f32_e32 v11, v11
	s_nop 0
	v_mul_f32_e32 v10, v11, v10
	v_fmac_f32_e32 v14, v10, v10
	v_and_b32_e32 v10, 0xffff0000, v4
	v_mul_f32_e32 v4, 0x3d372713, v10
	v_mul_f32_e32 v4, v4, v10
	v_mov_b32_e32 v12, v10
	v_fmac_f32_e32 v12, v4, v12
	v_mul_f32_e32 v4, 0x3f4c422a, v12
	v_mul_f32_e32 v4, -2.0, v4
	v_mul_f32_e32 v4, 0x3fb8aa3b, v4
	v_exp_f32_e32 v4, v4
	v_lshlrev_b32_e32 v11, 16, v5
	v_mov_b32_e32 v13, v11
	v_add_f32_e32 v4, 1.0, v4
	v_rcp_f32_e32 v12, v4
	v_mul_f32_e32 v4, 0x3d372713, v11
	v_mul_f32_e32 v4, v4, v11
	v_fmac_f32_e32 v13, v4, v13
	v_mul_f32_e32 v4, 0x3f4c422a, v13
	v_mul_f32_e32 v4, -2.0, v4
	v_mul_f32_e32 v4, 0x3fb8aa3b, v4
	v_exp_f32_e32 v4, v4
	s_nop 0
	v_add_f32_e32 v4, 1.0, v4
	v_rcp_f32_e32 v13, v4
	s_nop 0
	v_pk_mul_f32 v[10:11], v[12:13], v[10:11]
	s_nop 0
	v_pk_mul_f32 v[10:11], v[10:11], v[10:11]
	s_nop 0
	v_add_f32_e32 v4, v10, v14
	v_and_b32_e32 v10, 0xffff0000, v5
	v_add_f32_e32 v12, v11, v4
	v_mul_f32_e32 v4, 0x3d372713, v10
	v_mul_f32_e32 v4, v4, v10
	v_mov_b32_e32 v5, v10
	v_lshlrev_b32_e32 v11, 16, v6
	v_fmac_f32_e32 v5, v4, v5
	v_mul_f32_e32 v4, 0x3f4c422a, v5
; __device__ __forceinline__ float gelu_t(float x) { float u = 0.7978845608028654f * (x + 0.044715f * x * x * x); return x * __builtin_amdgcn_rcpf(1.f + __expf(-2.f * u)); }
; __device__ __forceinline__ void mixA_item(const Params& P, int layer, int idx, const bf16_t* z, bf16_t* y, char* lds) {
;     ...
;     for (int i = 0; i < 16; ++i) { float v[8]; unpack8(*(const u32x4*)(zr + half * 128 + i * 8), v);
; #pragma unroll
;       for (int e = 0; e < 8; ++e) { const float t = gelu_t(v[e]); ss += t * t; } }
	v_mul_f32_e32 v5, 0x3d372713, v11
	v_mul_f32_e32 v5, v5, v11
	v_mov_b32_e32 v13, v11
	v_fmac_f32_e32 v13, v5, v13
	v_mul_f32_e32 v5, 0x3f4c422a, v13
	v_mul_f32_e32 v4, -2.0, v4
	v_mul_f32_e32 v5, -2.0, v5
	v_mul_f32_e32 v4, 0x3fb8aa3b, v4
	v_mul_f32_e32 v5, 0x3fb8aa3b, v5
	v_exp_f32_e32 v4, v4
	v_exp_f32_e32 v5, v5
	v_add_f32_e32 v4, 1.0, v4
	v_add_f32_e32 v5, 1.0, v5
	v_rcp_f32_e32 v4, v4
	v_rcp_f32_e32 v5, v5
	s_nop 0
	v_pk_mul_f32 v[4:5], v[4:5], v[10:11]
	s_nop 0
	v_pk_mul_f32 v[4:5], v[4:5], v[4:5]
	s_nop 0
	v_add_f32_e32 v4, v4, v12
	v_add_f32_e32 v10, v5, v4
	v_and_b32_e32 v4, 0xffff0000, v6
	v_mul_f32_e32 v6, 0x3d372713, v4
	v_lshlrev_b32_e32 v5, 16, v7
	v_mul_f32_e32 v6, v6, v4
	v_mov_b32_e32 v7, v4
	v_fmac_f32_e32 v7, v6, v7
	v_mul_f32_e32 v6, 0x3f4c422a, v7
	v_mul_f32_e32 v7, 0x3d372713, v5
	v_mul_f32_e32 v7, v7, v5
	v_mov_b32_e32 v11, v5
	v_fmac_f32_e32 v11, v7, v11
	v_mul_f32_e32 v7, 0x3f4c422a, v11
	v_mul_f32_e32 v6, -2.0, v6
	v_mul_f32_e32 v7, -2.0, v7
	v_mul_f32_e32 v6, 0x3fb8aa3b, v6
	v_mul_f32_e32 v7, 0x3fb8aa3b, v7
	v_exp_f32_e32 v6, v6
	v_exp_f32_e32 v7, v7
	v_and_b32_e32 v11, 0xffff0000, v3
	v_add_f32_e32 v6, 1.0, v6
	v_add_f32_e32 v7, 1.0, v7
	v_rcp_f32_e32 v6, v6
	v_rcp_f32_e32 v7, v7
	s_nop 0
	v_pk_mul_f32 v[4:5], v[6:7], v[4:5]
	s_nop 0
	v_pk_mul_f32 v[4:5], v[4:5], v[4:5]
	s_nop 0
	v_add_f32_e32 v4, v4, v10
	v_add_f32_e32 v10, v5, v4
	v_mul_f32_e32 v4, 0x3d372713, v15
	v_mul_f32_e32 v4, v4, v15
	v_fma_f32 v4, v4, v15, v15
	v_mul_f32_e32 v4, 0x3f4c422a, v4
	v_mul_f32_e32 v4, -2.0, v4
	v_mul_f32_e32 v4, 0x3fb8aa3b, v4
	v_exp_f32_e32 v4, v4
	s_nop 0
	v_add_f32_e32 v4, 1.0, v4
	v_rcp_f32_e32 v4, v4
	s_nop 0
	v_mul_f32_e32 v4, v4, v15
	v_fmac_f32_e32 v10, v4, v4
	v_lshlrev_b32_e32 v4, 16, v0
	v_mul_f32_e32 v5, 0x3d372713, v4
	v_mul_f32_e32 v5, v5, v4
	v_fma_f32 v5, v5, v4, v4
	v_mul_f32_e32 v5, 0x3f4c422a, v5
	v_mul_f32_e32 v5, -2.0, v5
	v_mul_f32_e32 v5, 0x3fb8aa3b, v5
	v_exp_f32_e32 v5, v5
	s_nop 0
	v_add_f32_e32 v5, 1.0, v5
	v_rcp_f32_e32 v5, v5
	s_nop 0
	v_mul_f32_e32 v4, v5, v4
	v_fmac_f32_e32 v10, v4, v4
	v_and_b32_e32 v4, 0xffff0000, v0
	v_mul_f32_e32 v0, 0x3d372713, v4
	v_mul_f32_e32 v0, v0, v4
	v_mov_b32_e32 v6, v4
	v_fmac_f32_e32 v6, v0, v6
	v_mul_f32_e32 v0, 0x3f4c422a, v6
	v_mul_f32_e32 v0, -2.0, v0
	v_mul_f32_e32 v0, 0x3fb8aa3b, v0
	v_exp_f32_e32 v0, v0
	v_lshlrev_b32_e32 v5, 16, v1
	v_mov_b32_e32 v7, v5
	v_add_f32_e32 v0, 1.0, v0
	v_rcp_f32_e32 v6, v0
	v_mul_f32_e32 v0, 0x3d372713, v5
	v_mul_f32_e32 v0, v0, v5
	v_fmac_f32_e32 v7, v0, v7
	v_mul_f32_e32 v0, 0x3f4c422a, v7
	v_mul_f32_e32 v0, -2.0, v0
	v_mul_f32_e32 v0, 0x3fb8aa3b, v0
	v_exp_f32_e32 v0, v0
	s_nop 0
	v_add_f32_e32 v0, 1.0, v0
	v_rcp_f32_e32 v7, v0
	s_nop 0
	v_pk_mul_f32 v[4:5], v[6:7], v[4:5]
	s_nop 0
	v_pk_mul_f32 v[4:5], v[4:5], v[4:5]
	s_nop 0
	v_add_f32_e32 v0, v4, v10
	v_and_b32_e32 v4, 0xffff0000, v1
	v_add_f32_e32 v6, v5, v0
	v_mul_f32_e32 v0, 0x3d372713, v4
	v_mul_f32_e32 v0, v0, v4
	v_mov_b32_e32 v1, v4
	v_lshlrev_b32_e32 v5, 16, v2
	v_fmac_f32_e32 v1, v0, v1
	v_mul_f32_e32 v0, 0x3f4c422a, v1
	v_mul_f32_e32 v1, 0x3d372713, v5
	v_mul_f32_e32 v1, v1, v5
	v_mov_b32_e32 v7, v5
	v_fmac_f32_e32 v7, v1, v7
	v_mul_f32_e32 v1, 0x3f4c422a, v7
	v_mul_f32_e32 v0, -2.0, v0
	v_mul_f32_e32 v1, -2.0, v1
	v_mul_f32_e32 v0, 0x3fb8aa3b, v0
	v_mul_f32_e32 v1, 0x3fb8aa3b, v1
	v_exp_f32_e32 v0, v0
	v_exp_f32_e32 v1, v1
	v_add_f32_e32 v0, 1.0, v0
	v_add_f32_e32 v1, 1.0, v1
	v_rcp_f32_e32 v0, v0
	v_rcp_f32_e32 v1, v1
	s_nop 0
	v_pk_mul_f32 v[0:1], v[0:1], v[4:5]
	s_nop 0
	v_pk_mul_f32 v[0:1], v[0:1], v[0:1]
	s_nop 0
	v_add_f32_e32 v0, v0, v6
	v_add_f32_e32 v4, v1, v0
	v_and_b32_e32 v0, 0xffff0000, v2
	v_mul_f32_e32 v2, 0x3d372713, v0
	v_lshlrev_b32_e32 v1, 16, v3
	v_mul_f32_e32 v2, v2, v0
	v_mov_b32_e32 v3, v0
	v_fmac_f32_e32 v3, v2, v3
	v_mul_f32_e32 v2, 0x3f4c422a, v3
	v_mul_f32_e32 v3, 0x3d372713, v1
	v_mul_f32_e32 v3, v3, v1
	v_mov_b32_e32 v5, v1
	v_fmac_f32_e32 v5, v3, v5
	v_mul_f32_e32 v3, 0x3f4c422a, v5
	v_mul_f32_e32 v2, -2.0, v2
	v_mul_f32_e32 v3, -2.0, v3
	v_mul_f32_e32 v2, 0x3fb8aa3b, v2
	v_mul_f32_e32 v3, 0x3fb8aa3b, v3
	v_exp_f32_e32 v2, v2
	v_exp_f32_e32 v3, v3
	v_add_f32_e32 v2, 1.0, v2
	v_add_f32_e32 v3, 1.0, v3
	v_rcp_f32_e32 v2, v2
	v_rcp_f32_e32 v3, v3
	s_nop 0
	v_pk_mul_f32 v[0:1], v[2:3], v[0:1]
	s_nop 0
	v_pk_mul_f32 v[0:1], v[0:1], v[0:1]
	s_nop 0
	v_add_f32_e32 v0, v0, v4
	v_add_f32_e32 v10, v1, v0
	v_mul_f32_e32 v0, 0x3d372713, v11
	v_mul_f32_e32 v0, v0, v11
	v_fma_f32 v0, v0, v11, v11
	v_mul_f32_e32 v0, 0x3f4c422a, v0
	v_mul_f32_e32 v0, -2.0, v0
	v_mul_f32_e32 v0, 0x3fb8aa3b, v0
	v_exp_f32_e32 v0, v0
	s_nop 0
	v_add_f32_e32 v0, 1.0, v0
	v_rcp_f32_e32 v0, v0
	s_nop 0
	v_mul_f32_e32 v0, v0, v11
	v_fmac_f32_e32 v10, v0, v0
	s_cbranch_scc0 .LBB0_549
; __device__ __forceinline__ bf16_t f2bf(float f) { unsigned u = __float_as_uint(f); u += 0x7fffu + ((u >> 16) & 1u); return (bf16_t)(u >> 16); }
; __device__ __forceinline__ float gelu_t(float x) { float u = 0.7978845608028654f * (x + 0.044715f * x * x * x); return x * __builtin_amdgcn_rcpf(1.f + __expf(-2.f * u)); }
; __device__ __forceinline__ void mixA_item(const Params& P, int layer, int idx, const bf16_t* z, bf16_t* y, char* lds) {
;     ...
;     ss += __shfl_xor(ss, 1);
;     const float rs = rsqrtf(ss * (1.f / 256.f) + 1e-6f);
; #pragma unroll
;     for (int i = 0; i < 4; ++i) { float v[8]; unpack8(*(const u32x4*)(zr + g * 64 + half * 32 + i * 8), v);
; #pragma unroll
;       for (int e = 0; e < 8; ++e) { const int d = half * 32 + i * 8 + e; vT[d * 136 + s] = f2bf(gelu_t(v[e]) * rs * ng[g * 64 + d]); } }
	v_and_b32_e32 v0, 3, v42
	v_lshl_add_u32 v176, v0, 15, s17
	v_lshlrev_b32_e32 v0, 5, v43
	v_and_b32_e32 v36, 0xffffff80, v0
	v_or_b32_e32 v2, v29, v36
	v_mov_b64_e32 v[0:1], s[84:85]
	v_cmp_lt_i32_e32 vcc, v224, v218
	v_mad_i64_i32 v[0:1], s[30:31], v2, s43, v[0:1]
	s_nop 0
	v_cndmask_b32_e32 v2, v212, v224, vcc
	v_lshlrev_b32_e32 v2, 2, v2
	ds_bpermute_b32 v2, v2, v10
	s_mov_b32 s30, 0x800000
	v_and_b32_e32 v37, 3, v43
	v_lshlrev_b32_e32 v32, 6, v37
	v_lshlrev_b32_e32 v44, 5, v30
	s_waitcnt lgkmcnt(0)
	v_add_f32_e32 v2, v10, v2
	v_fmamk_f32 v2, v2, 0x3b800000, v178
	v_cmp_gt_f32_e32 vcc, s30, v2
	v_mul_f32_e32 v3, 0x4b800000, v2
	v_lshlrev_b32_e32 v29, 1, v29
	v_cndmask_b32_e32 v2, v2, v3, vcc
	v_rsq_f32_e32 v2, v2
	v_and_b32_e32 v38, 15, v28
	v_lshrrev_b32_sdwa v33, v232, v28 dst_sel:DWORD dst_unused:UNUSED_PAD src0_sel:DWORD src1_sel:BYTE_0
	v_readlane_b32 s30, v254, 45
	v_mul_f32_e32 v3, 0x45800000, v2
	v_cndmask_b32_e32 v31, v2, v3, vcc
	v_lshlrev_b32_e32 v2, 7, v37
	v_mov_b32_e32 v3, v177
	v_lshl_add_u64 v[0:1], v[0:1], 0, v[2:3]
	v_lshlrev_b32_e32 v2, 6, v30
	v_lshl_add_u64 v[8:9], v[0:1], 0, v[2:3]
	global_load_dwordx4 v[0:3], v[8:9], off offset:560
	global_load_dwordx4 v[4:7], v[8:9], off offset:544
	global_load_dwordx4 v[16:19], v[8:9], off offset:528
	s_nop 0
	global_load_dwordx4 v[8:11], v[8:9], off offset:512
	v_mul_u32_u24_e32 v30, 0x2200, v30
	v_add3_u32 v30, v60, v30, v29
	v_readlane_b32 s31, v254, 46
	s_movk_i32 s38, 0x1000
	s_waitcnt vmcnt(0)
	v_lshlrev_b32_e32 v12, 16, v8
	v_and_b32_e32 v45, 0xffff0000, v8
	v_mul_f32_e32 v8, 0x3d372713, v12
	v_mul_f32_e32 v8, v8, v12
	v_fma_f32 v8, v8, v12, v12
	v_mul_f32_e32 v8, 0x3f4c422a, v8
	v_mul_f32_e32 v8, -2.0, v8
	v_mul_f32_e32 v8, 0x3fb8aa3b, v8
	v_exp_f32_e32 v8, v8
	v_lshlrev_b32_e32 v46, 16, v9
	v_and_b32_e32 v47, 0xffff0000, v9
	v_lshlrev_b32_e32 v48, 16, v10
	v_add_f32_e32 v8, 1.0, v8
	v_rcp_f32_e32 v8, v8
	v_and_b32_e32 v41, 0xffff0000, v10
	v_lshlrev_b32_e32 v40, 16, v11
	v_and_b32_e32 v35, 0xffff0000, v11
	v_mul_f32_e32 v8, v8, v12
	v_mul_f32_e32 v49, v31, v8
	v_or_b32_e32 v8, v44, v32
	v_lshlrev_b32_e32 v34, 2, v8
	global_load_dwordx4 v[8:11], v34, s[34:35] offset:48
	global_load_dwordx4 v[12:15], v34, s[34:35] offset:32
	global_load_dwordx4 v[20:23], v34, s[34:35] offset:16
	global_load_dwordx4 v[24:27], v34, s[34:35]
	s_waitcnt vmcnt(0)
	v_mul_f32_e32 v24, v24, v49
	v_bfe_u32 v49, v24, 16, 1
	v_add3_u32 v24, v24, v49, s42
	ds_write_b16_d16_hi v30, v24
	v_mul_f32_e32 v30, 0x3d372713, v45
	v_mul_f32_e32 v30, v30, v45
	v_fma_f32 v30, v30, v45, v45
	v_mul_f32_e32 v30, 0x3f4c422a, v30
	v_mul_f32_e32 v30, -2.0, v30
	v_mul_f32_e32 v30, 0x3fb8aa3b, v30
	v_exp_f32_e32 v30, v30
	v_or_b32_e32 v24, 1, v44
	v_mul_u32_u24_e32 v24, 0x110, v24
	v_add3_u32 v24, v60, v24, v29
	v_add_f32_e32 v30, 1.0, v30
	v_rcp_f32_e32 v30, v30
	v_add_u32_e32 v44, 1, v33
	v_mul_f32_e32 v30, v30, v45
	v_mul_f32_e32 v30, v31, v30
	v_mul_f32_e32 v25, v25, v30
	v_bfe_u32 v30, v25, 16, 1
	v_add3_u32 v25, v25, v30, s42
	ds_write_b16_d16_hi v24, v25
	v_mul_f32_e32 v25, 0x3d372713, v46
	v_mul_f32_e32 v25, v25, v46
	v_fma_f32 v25, v25, v46, v46
	v_mul_f32_e32 v25, 0x3f4c422a, v25
	v_mul_f32_e32 v25, -2.0, v25
	v_mul_f32_e32 v25, 0x3fb8aa3b, v25
	v_exp_f32_e32 v25, v25
	s_nop 0
	v_add_f32_e32 v25, 1.0, v25
	v_rcp_f32_e32 v25, v25
	s_nop 0
	v_mul_f32_e32 v25, v25, v46
	v_mul_f32_e32 v25, v31, v25
	v_mul_f32_e32 v25, v26, v25
	v_bfe_u32 v26, v25, 16, 1
	v_add3_u32 v25, v25, v26, s42
	ds_write_b16_d16_hi v24, v25 offset:272
	v_mul_f32_e32 v25, 0x3d372713, v47
	v_mul_f32_e32 v25, v25, v47
	v_fma_f32 v25, v25, v47, v47
	v_mul_f32_e32 v25, 0x3f4c422a, v25
	v_mul_f32_e32 v25, -2.0, v25
	v_mul_f32_e32 v25, 0x3fb8aa3b, v25
	v_exp_f32_e32 v25, v25
	s_nop 0
	v_add_f32_e32 v25, 1.0, v25
	v_rcp_f32_e32 v25, v25
	s_nop 0
	v_mul_f32_e32 v25, v25, v47
	v_mul_f32_e32 v25, v31, v25
	v_mul_f32_e32 v25, v27, v25
	v_bfe_u32 v26, v25, 16, 1
	v_add3_u32 v25, v25, v26, s42
	ds_write_b16_d16_hi v24, v25 offset:544
	v_mul_f32_e32 v25, 0x3d372713, v48
	v_mul_f32_e32 v25, v25, v48
	v_fma_f32 v25, v25, v48, v48
	v_mul_f32_e32 v25, 0x3f4c422a, v25
	v_mul_f32_e32 v25, -2.0, v25
	v_mul_f32_e32 v25, 0x3fb8aa3b, v25
	v_exp_f32_e32 v25, v25
	v_and_b32_e32 v27, 0xffff0000, v4
	v_lshlrev_b32_e32 v26, 16, v5
	v_add_f32_e32 v25, 1.0, v25
	v_rcp_f32_e32 v25, v25
	s_nop 0
	v_mul_f32_e32 v25, v25, v48
	v_mul_f32_e32 v25, v31, v25
	v_mul_f32_e32 v20, v20, v25
	v_bfe_u32 v25, v20, 16, 1
	v_add3_u32 v20, v20, v25, s42
	ds_write_b16_d16_hi v24, v20 offset:816
	v_mul_f32_e32 v20, 0x3d372713, v41
	v_mul_f32_e32 v20, v20, v41
	v_fma_f32 v20, v20, v41, v41
	v_mul_f32_e32 v20, 0x3f4c422a, v20
	v_mul_f32_e32 v20, -2.0, v20
	v_mul_f32_e32 v20, 0x3fb8aa3b, v20
	v_exp_f32_e32 v20, v20
	s_nop 0
	v_add_f32_e32 v20, 1.0, v20
	v_rcp_f32_e32 v20, v20
	s_nop 0
	v_mul_f32_e32 v20, v20, v41
	v_mul_f32_e32 v20, v31, v20
	v_mul_f32_e32 v20, v21, v20
	v_bfe_u32 v21, v20, 16, 1
	v_add3_u32 v20, v20, v21, s42
	ds_write_b16_d16_hi v24, v20 offset:1088
	v_mul_f32_e32 v20, 0x3d372713, v40
	v_mul_f32_e32 v20, v20, v40
	v_fma_f32 v20, v20, v40, v40
	v_mul_f32_e32 v20, 0x3f4c422a, v20
	v_mul_f32_e32 v20, -2.0, v20
	v_mul_f32_e32 v20, 0x3fb8aa3b, v20
	v_exp_f32_e32 v20, v20
	s_nop 0
	v_add_f32_e32 v20, 1.0, v20
	v_rcp_f32_e32 v20, v20
	s_nop 0
	v_mul_f32_e32 v20, v20, v40
	v_mul_f32_e32 v20, v31, v20
	v_mul_f32_e32 v20, v22, v20
	v_bfe_u32 v21, v20, 16, 1
	v_add3_u32 v20, v20, v21, s42
	ds_write_b16_d16_hi v24, v20 offset:1360
	v_mul_f32_e32 v20, 0x3d372713, v35
	v_mul_f32_e32 v20, v20, v35
	v_fma_f32 v20, v20, v35, v35
	v_mul_f32_e32 v20, 0x3f4c422a, v20
	v_mul_f32_e32 v20, -2.0, v20
; __device__ __forceinline__ bf16_t f2bf(float f) { unsigned u = __float_as_uint(f); u += 0x7fffu + ((u >> 16) & 1u); return (bf16_t)(u >> 16); }
; __device__ __forceinline__ float gelu_t(float x) { float u = 0.7978845608028654f * (x + 0.044715f * x * x * x); return x * __builtin_amdgcn_rcpf(1.f + __expf(-2.f * u)); }
; __device__ __forceinline__ void mixA_item(const Params& P, int layer, int idx, const bf16_t* z, bf16_t* y, char* lds) {
;     ...
;     for (int i = 0; i < 4; ++i) { float v[8]; unpack8(*(const u32x4*)(zr + g * 64 + half * 32 + i * 8), v);
; #pragma unroll
;       for (int e = 0; e < 8; ++e) { const int d = half * 32 + i * 8 + e; vT[d * 136 + s] = f2bf(gelu_t(v[e]) * rs * ng[g * 64 + d]); } }
	v_mul_f32_e32 v20, 0x3fb8aa3b, v20
	v_exp_f32_e32 v20, v20
	v_lshlrev_b32_e32 v22, 16, v18
	v_and_b32_e32 v18, 0xffff0000, v18
	v_bfe_u32 v40, v28, 4, 2
	v_add_f32_e32 v20, 1.0, v20
	v_rcp_f32_e32 v20, v20
	s_nop 0
	v_mul_f32_e32 v20, v20, v35
	v_mul_f32_e32 v20, v31, v20
	v_mul_f32_e32 v20, v20, v23
	v_bfe_u32 v21, v20, 16, 1
	v_add3_u32 v20, v20, v21, s42
	ds_write_b16_d16_hi v24, v20 offset:1632
	v_lshlrev_b32_e32 v20, 16, v16
	v_mul_f32_e32 v25, 0x3d372713, v20
	v_mul_f32_e32 v25, v25, v20
	v_fma_f32 v25, v25, v20, v20
	v_mul_f32_e32 v25, 0x3f4c422a, v25
	v_mul_f32_e32 v25, -2.0, v25
	v_mul_f32_e32 v25, 0x3fb8aa3b, v25
	v_exp_f32_e32 v25, v25
	v_and_b32_e32 v16, 0xffff0000, v16
	v_lshlrev_b32_e32 v21, 16, v17
	v_and_b32_e32 v17, 0xffff0000, v17
	v_add_f32_e32 v25, 1.0, v25
	v_rcp_f32_e32 v25, v25
	v_lshlrev_b32_e32 v23, 16, v19
	v_and_b32_e32 v19, 0xffff0000, v19
	v_mul_f32_e32 v20, v25, v20
	v_mul_f32_e32 v20, v31, v20
	v_mul_f32_e32 v12, v12, v20
	v_bfe_u32 v20, v12, 16, 1
	v_add3_u32 v12, v12, v20, s42
	ds_write_b16_d16_hi v24, v12 offset:1904
	v_mul_f32_e32 v12, 0x3d372713, v16
	v_mul_f32_e32 v12, v12, v16
	v_fma_f32 v12, v12, v16, v16
	v_mul_f32_e32 v12, 0x3f4c422a, v12
	v_mul_f32_e32 v12, -2.0, v12
	v_mul_f32_e32 v12, 0x3fb8aa3b, v12
	v_exp_f32_e32 v12, v12
	v_and_b32_e32 v25, 0xffff0000, v5
	v_and_b32_e32 v20, 0xffff0000, v7
	v_add_f32_e32 v12, 1.0, v12
	v_rcp_f32_e32 v12, v12
	s_nop 0
	v_mul_f32_e32 v12, v12, v16
	v_mul_f32_e32 v12, v31, v12
	v_mul_f32_e32 v12, v13, v12
	v_bfe_u32 v13, v12, 16, 1
	v_add3_u32 v12, v12, v13, s42
	ds_write_b16_d16_hi v24, v12 offset:2176
	v_mul_f32_e32 v12, 0x3d372713, v21
	v_mul_f32_e32 v12, v12, v21
	v_fma_f32 v12, v12, v21, v21
	v_mul_f32_e32 v12, 0x3f4c422a, v12
	v_mul_f32_e32 v12, -2.0, v12
	v_mul_f32_e32 v12, 0x3fb8aa3b, v12
	v_exp_f32_e32 v12, v12
	s_nop 0
	v_add_f32_e32 v12, 1.0, v12
	v_rcp_f32_e32 v12, v12
	s_nop 0
	v_mul_f32_e32 v12, v12, v21
	v_mul_f32_e32 v12, v31, v12
	v_mul_f32_e32 v12, v14, v12
	v_bfe_u32 v13, v12, 16, 1
	v_add3_u32 v12, v12, v13, s42
	ds_write_b16_d16_hi v24, v12 offset:2448
	v_mul_f32_e32 v12, 0x3d372713, v17
	v_mul_f32_e32 v12, v12, v17
	v_fma_f32 v12, v12, v17, v17
	v_mul_f32_e32 v12, 0x3f4c422a, v12
	v_mul_f32_e32 v12, -2.0, v12
	v_mul_f32_e32 v12, 0x3fb8aa3b, v12
	v_exp_f32_e32 v12, v12
	v_lshlrev_b32_e32 v21, 16, v7
	v_add_f32_e32 v12, 1.0, v12
	v_rcp_f32_e32 v12, v12
	s_nop 0
	v_mul_f32_e32 v12, v12, v17
	v_mul_f32_e32 v12, v31, v12
	v_mul_f32_e32 v12, v15, v12
	v_bfe_u32 v13, v12, 16, 1
	v_add3_u32 v12, v12, v13, s42
	ds_write_b16_d16_hi v24, v12 offset:2720
	v_mul_f32_e32 v12, 0x3d372713, v22
	v_mul_f32_e32 v12, v12, v22
	v_fma_f32 v12, v12, v22, v22
	v_mul_f32_e32 v12, 0x3f4c422a, v12
	v_mul_f32_e32 v12, -2.0, v12
	v_mul_f32_e32 v12, 0x3fb8aa3b, v12
	v_exp_f32_e32 v12, v12
	s_nop 0
	v_add_f32_e32 v12, 1.0, v12
	v_rcp_f32_e32 v12, v12
	s_nop 0
	v_mul_f32_e32 v12, v12, v22
	v_mul_f32_e32 v12, v31, v12
	v_mul_f32_e32 v8, v8, v12
	v_bfe_u32 v12, v8, 16, 1
	v_add3_u32 v8, v8, v12, s42
	ds_write_b16_d16_hi v24, v8 offset:2992
	v_mul_f32_e32 v8, 0x3d372713, v18
	v_mul_f32_e32 v8, v8, v18
	v_fma_f32 v8, v8, v18, v18
	v_mul_f32_e32 v8, 0x3f4c422a, v8
	v_mul_f32_e32 v8, -2.0, v8
	v_mul_f32_e32 v8, 0x3fb8aa3b, v8
	v_exp_f32_e32 v8, v8
	v_and_b32_e32 v22, 0xffff0000, v6
	v_add_f32_e32 v8, 1.0, v8
	v_rcp_f32_e32 v8, v8
	s_nop 0
	v_mul_f32_e32 v8, v8, v18
	v_mul_f32_e32 v8, v31, v8
	v_mul_f32_e32 v8, v9, v8
	v_bfe_u32 v9, v8, 16, 1
	v_add3_u32 v8, v8, v9, s42
	ds_write_b16_d16_hi v24, v8 offset:3264
	v_mul_f32_e32 v8, 0x3d372713, v23
	v_mul_f32_e32 v8, v8, v23
	v_fma_f32 v8, v8, v23, v23
	v_mul_f32_e32 v8, 0x3f4c422a, v8
	v_mul_f32_e32 v8, -2.0, v8
	v_mul_f32_e32 v8, 0x3fb8aa3b, v8
	v_exp_f32_e32 v8, v8
	s_nop 0
	v_add_f32_e32 v8, 1.0, v8
	v_rcp_f32_e32 v8, v8
	s_nop 0
	v_mul_f32_e32 v8, v8, v23
	v_mul_f32_e32 v8, v31, v8
	v_mul_f32_e32 v8, v10, v8
	v_bfe_u32 v9, v8, 16, 1
	v_add3_u32 v8, v8, v9, s42
	ds_write_b16_d16_hi v24, v8 offset:3536
	v_mul_f32_e32 v8, 0x3d372713, v19
	v_mul_f32_e32 v8, v8, v19
	v_fma_f32 v8, v8, v19, v19
	v_mul_f32_e32 v8, 0x3f4c422a, v8
	v_mul_f32_e32 v8, -2.0, v8
	v_mul_f32_e32 v8, 0x3fb8aa3b, v8
	v_exp_f32_e32 v8, v8
	v_lshlrev_b32_e32 v23, 16, v6
	v_add_f32_e32 v8, 1.0, v8
	v_rcp_f32_e32 v8, v8
	s_nop 0
	v_mul_f32_e32 v8, v8, v19
	v_mul_f32_e32 v8, v31, v8
	v_mul_f32_e32 v8, v8, v11
	v_bfe_u32 v9, v8, 16, 1
	v_add3_u32 v8, v8, v9, s42
	ds_write_b16_d16_hi v24, v8 offset:3808
	v_lshlrev_b32_e32 v8, 16, v4
	v_mul_f32_e32 v4, 0x3d372713, v8
	v_mul_f32_e32 v4, v4, v8
	v_fma_f32 v4, v4, v8, v8
	v_mul_f32_e32 v4, 0x3f4c422a, v4
	v_mul_f32_e32 v4, -2.0, v4
	v_mul_f32_e32 v4, 0x3fb8aa3b, v4
	v_exp_f32_e32 v4, v4
	s_nop 0
	v_add_f32_e32 v4, 1.0, v4
	v_rcp_f32_e32 v4, v4
	s_nop 0
	v_mul_f32_e32 v4, v4, v8
	v_mul_f32_e32 v29, v31, v4
	global_load_dwordx4 v[4:7], v34, s[34:35] offset:112
	global_load_dwordx4 v[8:11], v34, s[34:35] offset:96
	global_load_dwordx4 v[12:15], v34, s[34:35] offset:80
	global_load_dwordx4 v[16:19], v34, s[34:35] offset:64
	s_waitcnt vmcnt(0)
; __device__ __forceinline__ bf16_t f2bf(float f) { unsigned u = __float_as_uint(f); u += 0x7fffu + ((u >> 16) & 1u); return (bf16_t)(u >> 16); }
; __device__ __forceinline__ float gelu_t(float x) { float u = 0.7978845608028654f * (x + 0.044715f * x * x * x); return x * __builtin_amdgcn_rcpf(1.f + __expf(-2.f * u)); }
; __device__ __forceinline__ void mixA_item(const Params& P, int layer, int idx, const bf16_t* z, bf16_t* y, char* lds) {
;     ...
;     for (int i = 0; i < 4; ++i) { float v[8]; unpack8(*(const u32x4*)(zr + g * 64 + half * 32 + i * 8), v);
; #pragma unroll
;       for (int e = 0; e < 8; ++e) { const int d = half * 32 + i * 8 + e; vT[d * 136 + s] = f2bf(gelu_t(v[e]) * rs * ng[g * 64 + d]); } }
	v_mul_f32_e32 v16, v16, v29
	v_bfe_u32 v29, v16, 16, 1
	v_add3_u32 v16, v16, v29, s42
	ds_write_b16_d16_hi v24, v16 offset:4080
	v_mul_f32_e32 v16, 0x3d372713, v27
	v_mul_f32_e32 v16, v16, v27
	v_fma_f32 v16, v16, v27, v27
	v_mul_f32_e32 v16, 0x3f4c422a, v16
	v_mul_f32_e32 v16, -2.0, v16
	v_mul_f32_e32 v16, 0x3fb8aa3b, v16
	v_exp_f32_e32 v16, v16
	s_nop 0
	v_add_f32_e32 v16, 1.0, v16
	v_rcp_f32_e32 v16, v16
	s_nop 0
	v_mul_f32_e32 v16, v16, v27
	v_mul_f32_e32 v16, v31, v16
	v_mul_f32_e32 v16, v17, v16
	v_bfe_u32 v17, v16, 16, 1
	v_add3_u32 v16, v16, v17, s42
	ds_write_b16_d16_hi v24, v16 offset:4352
	v_mul_f32_e32 v16, 0x3d372713, v26
	v_mul_f32_e32 v16, v16, v26
	v_fma_f32 v16, v16, v26, v26
	v_mul_f32_e32 v16, 0x3f4c422a, v16
	v_mul_f32_e32 v16, -2.0, v16
	v_mul_f32_e32 v16, 0x3fb8aa3b, v16
	v_exp_f32_e32 v16, v16
	s_nop 0
	v_add_f32_e32 v16, 1.0, v16
	v_rcp_f32_e32 v16, v16
	s_nop 0
	v_mul_f32_e32 v16, v16, v26
	v_mul_f32_e32 v16, v31, v16
	v_mul_f32_e32 v16, v18, v16
	v_bfe_u32 v17, v16, 16, 1
	v_add3_u32 v16, v16, v17, s42
	ds_write_b16_d16_hi v24, v16 offset:4624
	v_mul_f32_e32 v16, 0x3d372713, v25
	v_mul_f32_e32 v16, v16, v25
	v_fma_f32 v16, v16, v25, v25
	v_mul_f32_e32 v16, 0x3f4c422a, v16
	v_mul_f32_e32 v16, -2.0, v16
	v_mul_f32_e32 v16, 0x3fb8aa3b, v16
	v_exp_f32_e32 v16, v16
	s_nop 0
	v_add_f32_e32 v16, 1.0, v16
	v_rcp_f32_e32 v16, v16
	s_nop 0
	v_mul_f32_e32 v16, v16, v25
	v_mul_f32_e32 v16, v31, v16
	v_mul_f32_e32 v16, v19, v16
	v_bfe_u32 v17, v16, 16, 1
	v_add3_u32 v16, v16, v17, s42
	ds_write_b16_d16_hi v24, v16 offset:4896
	v_mul_f32_e32 v16, 0x3d372713, v23
	v_mul_f32_e32 v16, v16, v23
	v_fma_f32 v16, v16, v23, v23
	v_mul_f32_e32 v16, 0x3f4c422a, v16
	v_mul_f32_e32 v16, -2.0, v16
	v_mul_f32_e32 v16, 0x3fb8aa3b, v16
	v_exp_f32_e32 v16, v16
	s_nop 0
	v_add_f32_e32 v16, 1.0, v16
	v_rcp_f32_e32 v16, v16
	s_nop 0
	v_mul_f32_e32 v16, v16, v23
	v_mul_f32_e32 v16, v31, v16
	v_mul_f32_e32 v12, v12, v16
	v_bfe_u32 v16, v12, 16, 1
	v_add3_u32 v12, v12, v16, s42
	ds_write_b16_d16_hi v24, v12 offset:5168
	v_mul_f32_e32 v12, 0x3d372713, v22
	v_mul_f32_e32 v12, v12, v22
	v_fma_f32 v12, v12, v22, v22
	v_mul_f32_e32 v12, 0x3f4c422a, v12
	v_mul_f32_e32 v12, -2.0, v12
	v_mul_f32_e32 v12, 0x3fb8aa3b, v12
	v_exp_f32_e32 v12, v12
	s_nop 0
	v_add_f32_e32 v12, 1.0, v12
	v_rcp_f32_e32 v12, v12
	s_nop 0
	v_mul_f32_e32 v12, v12, v22
	v_mul_f32_e32 v12, v31, v12
	v_mul_f32_e32 v12, v13, v12
	v_bfe_u32 v13, v12, 16, 1
	v_add3_u32 v12, v12, v13, s42
	ds_write_b16_d16_hi v24, v12 offset:5440
	v_mul_f32_e32 v12, 0x3d372713, v21
	v_mul_f32_e32 v12, v12, v21
	v_fma_f32 v12, v12, v21, v21
	v_mul_f32_e32 v12, 0x3f4c422a, v12
	v_mul_f32_e32 v12, -2.0, v12
	v_mul_f32_e32 v12, 0x3fb8aa3b, v12
	v_exp_f32_e32 v12, v12
	s_nop 0
	v_add_f32_e32 v12, 1.0, v12
	v_rcp_f32_e32 v12, v12
	s_nop 0
	v_mul_f32_e32 v12, v12, v21
	v_mul_f32_e32 v12, v31, v12
	v_mul_f32_e32 v12, v14, v12
	v_bfe_u32 v13, v12, 16, 1
	v_add3_u32 v12, v12, v13, s42
	ds_write_b16_d16_hi v24, v12 offset:5712
	v_mul_f32_e32 v12, 0x3d372713, v20
	v_mul_f32_e32 v12, v12, v20
	v_fma_f32 v12, v12, v20, v20
	v_mul_f32_e32 v12, 0x3f4c422a, v12
	v_mul_f32_e32 v12, -2.0, v12
	v_mul_f32_e32 v12, 0x3fb8aa3b, v12
	v_exp_f32_e32 v12, v12
	v_lshlrev_b32_e32 v14, 16, v2
	v_and_b32_e32 v2, 0xffff0000, v2
	v_add_f32_e32 v12, 1.0, v12
	v_rcp_f32_e32 v12, v12
	s_nop 0
	v_mul_f32_e32 v12, v12, v20
	v_mul_f32_e32 v12, v31, v12
	v_mul_f32_e32 v12, v12, v15
	v_bfe_u32 v13, v12, 16, 1
	v_add3_u32 v12, v12, v13, s42
	ds_write_b16_d16_hi v24, v12 offset:5984
	v_lshlrev_b32_e32 v12, 16, v0
	v_mul_f32_e32 v16, 0x3d372713, v12
	v_mul_f32_e32 v16, v16, v12
	v_fma_f32 v16, v16, v12, v12
	v_mul_f32_e32 v16, 0x3f4c422a, v16
	v_mul_f32_e32 v16, -2.0, v16
	v_mul_f32_e32 v16, 0x3fb8aa3b, v16
	v_exp_f32_e32 v16, v16
	v_and_b32_e32 v0, 0xffff0000, v0
	v_lshlrev_b32_e32 v13, 16, v1
	v_and_b32_e32 v1, 0xffff0000, v1
	v_add_f32_e32 v16, 1.0, v16
	v_rcp_f32_e32 v16, v16
	v_lshlrev_b32_e32 v15, 16, v3
	v_and_b32_e32 v3, 0xffff0000, v3
	v_mul_f32_e32 v12, v16, v12
	v_mul_f32_e32 v12, v31, v12
	v_mul_f32_e32 v8, v8, v12
	v_bfe_u32 v12, v8, 16, 1
	v_add3_u32 v8, v8, v12, s42
	ds_write_b16_d16_hi v24, v8 offset:6256
	v_mul_f32_e32 v8, 0x3d372713, v0
; __device__ __forceinline__ bf16_t f2bf(float f) { unsigned u = __float_as_uint(f); u += 0x7fffu + ((u >> 16) & 1u); return (bf16_t)(u >> 16); }
; __device__ __forceinline__ float gelu_t(float x) { float u = 0.7978845608028654f * (x + 0.044715f * x * x * x); return x * __builtin_amdgcn_rcpf(1.f + __expf(-2.f * u)); }
; __device__ __forceinline__ void mixA_item(const Params& P, int layer, int idx, const bf16_t* z, bf16_t* y, char* lds) {
;     ...
;     for (int i = 0; i < 4; ++i) { float v[8]; unpack8(*(const u32x4*)(zr + g * 64 + half * 32 + i * 8), v);
; #pragma unroll
;       for (int e = 0; e < 8; ++e) { const int d = half * 32 + i * 8 + e; vT[d * 136 + s] = f2bf(gelu_t(v[e]) * rs * ng[g * 64 + d]); } }
;   }
;   __syncthreads();
;   const bf16_t* W = (const bf16_t*)(P.ws + OFF_SGUW) + (size_t)((layer * 4 + g) * 128) * 128;
;   f32x4 acc[2][4] = {};
	v_mul_f32_e32 v8, v8, v0
	v_fma_f32 v8, v8, v0, v0
	v_mul_f32_e32 v8, 0x3f4c422a, v8
	v_mul_f32_e32 v8, -2.0, v8
	v_mul_f32_e32 v8, 0x3fb8aa3b, v8
	v_exp_f32_e32 v8, v8
	s_nop 0
	v_add_f32_e32 v8, 1.0, v8
	v_rcp_f32_e32 v8, v8
	s_nop 0
	v_mul_f32_e32 v0, v8, v0
	v_mul_f32_e32 v0, v31, v0
	v_mul_f32_e32 v0, v9, v0
	v_bfe_u32 v8, v0, 16, 1
	v_add3_u32 v0, v0, v8, s42
	ds_write_b16_d16_hi v24, v0 offset:6528
	v_mul_f32_e32 v0, 0x3d372713, v13
	v_mul_f32_e32 v0, v0, v13
	v_fma_f32 v0, v0, v13, v13
	v_mul_f32_e32 v0, 0x3f4c422a, v0
	v_mul_f32_e32 v0, -2.0, v0
	v_mul_f32_e32 v0, 0x3fb8aa3b, v0
	v_exp_f32_e32 v0, v0
	s_nop 0
	v_add_f32_e32 v0, 1.0, v0
	v_rcp_f32_e32 v0, v0
	s_nop 0
	v_mul_f32_e32 v0, v0, v13
	v_mul_f32_e32 v0, v31, v0
	v_mul_f32_e32 v0, v10, v0
	v_bfe_u32 v8, v0, 16, 1
	v_add3_u32 v0, v0, v8, s42
	ds_write_b16_d16_hi v24, v0 offset:6800
	v_mul_f32_e32 v0, 0x3d372713, v1
	v_mul_f32_e32 v0, v0, v1
	v_fma_f32 v0, v0, v1, v1
	v_mul_f32_e32 v0, 0x3f4c422a, v0
	v_mul_f32_e32 v0, -2.0, v0
	v_mul_f32_e32 v0, 0x3fb8aa3b, v0
	v_exp_f32_e32 v0, v0
	s_nop 0
	v_add_f32_e32 v0, 1.0, v0
	v_rcp_f32_e32 v0, v0
	s_nop 0
	v_mul_f32_e32 v0, v0, v1
	v_mul_f32_e32 v0, v31, v0
	v_mul_f32_e32 v0, v11, v0
	v_bfe_u32 v1, v0, 16, 1
	v_add3_u32 v0, v0, v1, s42
	ds_write_b16_d16_hi v24, v0 offset:7072
	v_mul_f32_e32 v0, 0x3d372713, v14
	v_mul_f32_e32 v0, v0, v14
	v_fma_f32 v0, v0, v14, v14
	v_mul_f32_e32 v0, 0x3f4c422a, v0
	v_mul_f32_e32 v0, -2.0, v0
	v_mul_f32_e32 v0, 0x3fb8aa3b, v0
	v_exp_f32_e32 v0, v0
	s_nop 0
	v_add_f32_e32 v0, 1.0, v0
	v_rcp_f32_e32 v0, v0
	s_nop 0
	v_mul_f32_e32 v0, v0, v14
	v_mul_f32_e32 v0, v31, v0
	v_mul_f32_e32 v0, v4, v0
	v_bfe_u32 v1, v0, 16, 1
	v_add3_u32 v0, v0, v1, s42
	ds_write_b16_d16_hi v24, v0 offset:7344
	v_mul_f32_e32 v0, 0x3d372713, v2
	v_mul_f32_e32 v0, v0, v2
	v_fma_f32 v0, v0, v2, v2
	v_mul_f32_e32 v0, 0x3f4c422a, v0
	v_mul_f32_e32 v0, -2.0, v0
	v_mul_f32_e32 v0, 0x3fb8aa3b, v0
	v_exp_f32_e32 v0, v0
	s_nop 0
	v_add_f32_e32 v0, 1.0, v0
	v_rcp_f32_e32 v0, v0
	s_nop 0
	v_mul_f32_e32 v0, v0, v2
	v_mul_f32_e32 v0, v31, v0
	v_mul_f32_e32 v0, v5, v0
	v_bfe_u32 v1, v0, 16, 1
	v_add3_u32 v0, v0, v1, s42
	ds_write_b16_d16_hi v24, v0 offset:7616
	v_mul_f32_e32 v0, 0x3d372713, v15
	v_mul_f32_e32 v0, v0, v15
	v_fma_f32 v0, v0, v15, v15
	v_mul_f32_e32 v0, 0x3f4c422a, v0
	v_mul_f32_e32 v0, -2.0, v0
	v_mul_f32_e32 v0, 0x3fb8aa3b, v0
	v_exp_f32_e32 v0, v0
	v_lshlrev_b32_e32 v2, 13, v33
	v_add_f32_e32 v0, 1.0, v0
	v_rcp_f32_e32 v0, v0
	s_nop 0
	v_mul_f32_e32 v0, v0, v15
	v_mul_f32_e32 v0, v31, v0
	v_mul_f32_e32 v0, v6, v0
	v_bfe_u32 v1, v0, 16, 1
	v_add3_u32 v0, v0, v1, s42
	ds_write_b16_d16_hi v24, v0 offset:7888
	v_mul_f32_e32 v0, 0x3d372713, v3
	v_mul_f32_e32 v0, v0, v3
	v_fma_f32 v0, v0, v3, v3
	v_mul_f32_e32 v0, 0x3f4c422a, v0
	v_mul_f32_e32 v0, -2.0, v0
	v_mul_f32_e32 v0, 0x3fb8aa3b, v0
	v_exp_f32_e32 v0, v0
	s_nop 0
	v_add_f32_e32 v0, 1.0, v0
	v_rcp_f32_e32 v0, v0
	s_nop 0
	v_mul_f32_e32 v0, v0, v3
	v_mul_f32_e32 v0, v31, v0
	v_mul_f32_e32 v0, v0, v7
	v_bfe_u32 v1, v0, 16, 1
	v_add3_u32 v0, v0, v1, s42
	ds_write_b16_d16_hi v24, v0 offset:8160
	v_mul_u32_u24_e32 v0, 0x110, v38
	v_lshlrev_b32_e32 v1, 4, v40
	v_add3_u32 v41, v60, v1, v0
	v_lshlrev_b32_e32 v0, 8, v38
	v_or3_b32 v0, v2, v0, v1
	v_mov_b32_e32 v1, v177
	v_lshl_add_u64 v[0:1], v[0:1], 0, v[176:177]
	v_mov_b32_e32 v24, 0
	v_lshl_add_u64 v[34:35], s[30:31], 0, v[0:1]
	s_mov_b64 s[30:31], 0
	v_mov_b32_e32 v25, v24
	v_mov_b32_e32 v26, v24
	v_mov_b32_e32 v27, v24
	v_mov_b32_e32 v28, v24
	v_mov_b32_e32 v29, v24
	v_mov_b32_e32 v30, v24
	v_mov_b32_e32 v31, v24
	v_mov_b32_e32 v20, v24
	v_mov_b32_e32 v21, v24
	v_mov_b32_e32 v22, v24
	v_mov_b32_e32 v23, v24
	v_mov_b32_e32 v16, v24
	v_mov_b32_e32 v17, v24
	v_mov_b32_e32 v18, v24
	v_mov_b32_e32 v19, v24
	v_mov_b32_e32 v12, v24
	v_mov_b32_e32 v13, v24
	v_mov_b32_e32 v14, v24
	v_mov_b32_e32 v15, v24
	v_mov_b32_e32 v8, v24
	v_mov_b32_e32 v9, v24
	v_mov_b32_e32 v10, v24
	v_mov_b32_e32 v11, v24
	v_mov_b32_e32 v4, v24
	v_mov_b32_e32 v5, v24
	v_mov_b32_e32 v6, v24
	v_mov_b32_e32 v7, v24
	v_mov_b32_e32 v0, v24
	v_mov_b32_e32 v1, v24
	v_mov_b32_e32 v2, v24
	v_mov_b32_e32 v3, v24
	s_waitcnt lgkmcnt(0)
	s_barrier

; __device__ __forceinline__ unsigned pk2(float lo, float hi) { const f32x2v v = {lo, hi}; const bf16x2v r = __builtin_convertvector(v, bf16x2v); return __builtin_bit_cast(unsigned, r); }
; __device__ __forceinline__ void prep_phase(const Params& P, char* ldsc) {
;     ...
;   for (int i = gtid; i < 2 * M_TOK * 256 / 4; i += gn) { const float4 v = ((const float4*)P.p)[i]; uint2 o; o.x = pk2(v.x, v.y); o.y = pk2(v.z, v.w); ((uint2*)(ws + OFF_PBF))[i] = o; }
.LBB0_1007:
	s_mov_b32 s16, 3
	global_load_dwordx4 v[6:9], v[2:3], off offset:-8
	v_lshl_add_u64 v[2:3], v[2:3], 0, s[36:37]
	global_load_dwordx4 v[10:13], v[2:3], off offset:-8
	v_lshl_add_u64 v[2:3], v[2:3], 0, s[36:37]
	global_load_dwordx4 v[14:17], v[2:3], off offset:-8
	v_lshl_add_u64 v[2:3], v[2:3], 0, s[36:37]
	global_load_dwordx4 v[18:21], v[2:3], off offset:-8
	v_lshl_add_u64 v[2:3], v[2:3], 0, s[36:37]
	global_load_dwordx4 v[22:25], v[2:3], off offset:-8
	v_lshl_add_u64 v[2:3], v[2:3], 0, s[36:37]
	global_load_dwordx4 v[26:29], v[2:3], off offset:-8
	v_lshl_add_u64 v[2:3], v[2:3], 0, s[36:37]
	global_load_dwordx4 v[30:33], v[2:3], off offset:-8
	v_lshl_add_u64 v[2:3], v[2:3], 0, s[36:37]
	global_load_dwordx4 v[34:37], v[2:3], off offset:-8
	v_lshl_add_u64 v[2:3], v[2:3], 0, s[36:37]
	s_waitcnt vmcnt(7)
	v_cvt_pk_bf16_f32 v6, v6, v7
	v_cvt_pk_bf16_f32 v7, v8, v9
	global_store_dwordx2 v[4:5], v[6:7], off
	v_lshl_add_u64 v[4:5], v[4:5], 0, s[38:39]
	s_waitcnt vmcnt(7)
	v_cvt_pk_bf16_f32 v10, v10, v11
	v_cvt_pk_bf16_f32 v11, v12, v13
	global_store_dwordx2 v[4:5], v[10:11], off
	v_lshl_add_u64 v[4:5], v[4:5], 0, s[38:39]
	s_waitcnt vmcnt(7)
	v_cvt_pk_bf16_f32 v14, v14, v15
	v_cvt_pk_bf16_f32 v15, v16, v17
	global_store_dwordx2 v[4:5], v[14:15], off
	v_lshl_add_u64 v[4:5], v[4:5], 0, s[38:39]
	s_waitcnt vmcnt(7)
	v_cvt_pk_bf16_f32 v18, v18, v19
	v_cvt_pk_bf16_f32 v19, v20, v21
	global_store_dwordx2 v[4:5], v[18:19], off
	v_lshl_add_u64 v[4:5], v[4:5], 0, s[38:39]
.Lpconv_loop:
	global_load_dwordx4 v[6:9], v[2:3], off offset:-8
	v_lshl_add_u64 v[2:3], v[2:3], 0, s[36:37]
	global_load_dwordx4 v[10:13], v[2:3], off offset:-8
	v_lshl_add_u64 v[2:3], v[2:3], 0, s[36:37]
	global_load_dwordx4 v[14:17], v[2:3], off offset:-8
	v_lshl_add_u64 v[2:3], v[2:3], 0, s[36:37]
	global_load_dwordx4 v[18:21], v[2:3], off offset:-8
	v_lshl_add_u64 v[2:3], v[2:3], 0, s[36:37]
	s_waitcnt vmcnt(11)
	v_cvt_pk_bf16_f32 v22, v22, v23
	v_cvt_pk_bf16_f32 v23, v24, v25
	global_store_dwordx2 v[4:5], v[22:23], off
	v_lshl_add_u64 v[4:5], v[4:5], 0, s[38:39]
	s_waitcnt vmcnt(11)
	v_cvt_pk_bf16_f32 v26, v26, v27
	v_cvt_pk_bf16_f32 v27, v28, v29
	global_store_dwordx2 v[4:5], v[26:27], off
	v_lshl_add_u64 v[4:5], v[4:5], 0, s[38:39]
	s_waitcnt vmcnt(11)
	v_cvt_pk_bf16_f32 v30, v30, v31
	v_cvt_pk_bf16_f32 v31, v32, v33
	global_store_dwordx2 v[4:5], v[30:31], off
	v_lshl_add_u64 v[4:5], v[4:5], 0, s[38:39]
	s_waitcnt vmcnt(11)
	v_cvt_pk_bf16_f32 v34, v34, v35
	v_cvt_pk_bf16_f32 v35, v36, v37
	global_store_dwordx2 v[4:5], v[34:35], off
	v_lshl_add_u64 v[4:5], v[4:5], 0, s[38:39]
	global_load_dwordx4 v[22:25], v[2:3], off offset:-8
	v_lshl_add_u64 v[2:3], v[2:3], 0, s[36:37]
	global_load_dwordx4 v[26:29], v[2:3], off offset:-8
	v_lshl_add_u64 v[2:3], v[2:3], 0, s[36:37]
	global_load_dwordx4 v[30:33], v[2:3], off offset:-8
	v_lshl_add_u64 v[2:3], v[2:3], 0, s[36:37]
	global_load_dwordx4 v[34:37], v[2:3], off offset:-8
	v_lshl_add_u64 v[2:3], v[2:3], 0, s[36:37]
	s_waitcnt vmcnt(11)
	v_cvt_pk_bf16_f32 v6, v6, v7
	v_cvt_pk_bf16_f32 v7, v8, v9
	global_store_dwordx2 v[4:5], v[6:7], off
	v_lshl_add_u64 v[4:5], v[4:5], 0, s[38:39]
	s_waitcnt vmcnt(11)
	v_cvt_pk_bf16_f32 v10, v10, v11
	v_cvt_pk_bf16_f32 v11, v12, v13
	global_store_dwordx2 v[4:5], v[10:11], off
	v_lshl_add_u64 v[4:5], v[4:5], 0, s[38:39]
	s_waitcnt vmcnt(11)
	v_cvt_pk_bf16_f32 v14, v14, v15
	v_cvt_pk_bf16_f32 v15, v16, v17
	global_store_dwordx2 v[4:5], v[14:15], off
	v_lshl_add_u64 v[4:5], v[4:5], 0, s[38:39]
	s_waitcnt vmcnt(11)
	v_cvt_pk_bf16_f32 v18, v18, v19
	v_cvt_pk_bf16_f32 v19, v20, v21
	global_store_dwordx2 v[4:5], v[18:19], off
	v_lshl_add_u64 v[4:5], v[4:5], 0, s[38:39]
	s_sub_u32 s16, s16, 1
	s_cmp_lg_u32 s16, 0
	s_cbranch_scc1 .Lpconv_loop
	s_waitcnt vmcnt(7)
	v_cvt_pk_bf16_f32 v22, v22, v23
	v_cvt_pk_bf16_f32 v23, v24, v25
	global_store_dwordx2 v[4:5], v[22:23], off
	v_lshl_add_u64 v[4:5], v[4:5], 0, s[38:39]
	s_waitcnt vmcnt(7)
	v_cvt_pk_bf16_f32 v26, v26, v27
	v_cvt_pk_bf16_f32 v27, v28, v29
	global_store_dwordx2 v[4:5], v[26:27], off
	v_lshl_add_u64 v[4:5], v[4:5], 0, s[38:39]
	s_waitcnt vmcnt(7)
	v_cvt_pk_bf16_f32 v30, v30, v31
	v_cvt_pk_bf16_f32 v31, v32, v33
	global_store_dwordx2 v[4:5], v[30:31], off
	v_lshl_add_u64 v[4:5], v[4:5], 0, s[38:39]
	s_waitcnt vmcnt(7)
	v_cvt_pk_bf16_f32 v34, v34, v35
	v_cvt_pk_bf16_f32 v35, v36, v37
	global_store_dwordx2 v[4:5], v[34:35], off
	v_lshl_add_u64 v[4:5], v[4:5], 0, s[38:39]
